# P1: B-fragment tuples moved to bank-0-aligned registers as well (both MFMA sources on bank 0, accumulators on bank 2, like the P3 loop)
# speedup vs baseline: 1.0049x; 1.0049x over previous
; #define PG8_LAS __attribute__((address_space(3)))
; #define PG8_STAGE(bufoff, gbase, voff) do { _Pragma("unroll") for (int _i = 0; _i < 2; ++_i) \
;         __builtin_amdgcn_global_load_lds((const unsigned*)((const char*)(gbase) + (voff)[_i]), (PG8_LAS unsigned*)(lds + (bufoff) + ldsw + _i * 8192), 16, 0, 0); } while (0)
; #define PG8_WAIT_V(n) asm volatile("s_waitcnt vmcnt(" #n ")" ::: "memory")
; #define PG8_WAIT_L(n) asm volatile("s_waitcnt lgkmcnt(" #n ")" ::: "memory")
; template <class Epi, class Sched, bool ALIGN_EPI = false, bool SP2 = false, bool RS = false, bool BPRE = false>
; __device__ __forceinline__ void gemm_phase(PG8_LAS unsigned char* lds, const Gemm g, const Sched& S, const Epi& E, const float* rs_ss = nullptr, PG8_LAS float* rs_tab = nullptr) {
;     ...
;         const char* nA = has_next ? (const char*)g.A + (size_t)nxt.pm * tstep : cA; const char* nB = has_next ? (const char*)g.Bt + (size_t)nxt.pn * tstep : cB;
;         for (int t = 0; t < nt; t += 2) {
;             const bool last = (t == nt - 2);
;             if constexpr (RS) { if (t == 16 || t == 32) { const PG8_LAS float* tp = rs_tab + (ui & 1) * 768 + (t == 32 ? 256 : 0);
;                 _Pragma("unroll") for (int a = 0; a < 2; ++a) _Pragma("unroll") for (int m = 0; m < 4; ++m) { const float f = tp[a * HALF + wr * 64 + m * 16 + fr];
;                     _Pragma("unroll") for (int b = 0; b < 2; ++b) _Pragma("unroll") for (int n = 0; n < 2; ++n) acc[a][b][m][n] = acc[a][b][m][n] * f; } } }
;             const char* a1 = cA + (size_t)(t + 1) * kstep;
;             const char* a2 = last ? nA : cA + (size_t)(t + 2) * kstep; const char* b2 = last ? nB : cB + (size_t)(t + 2) * kstep;
;             const char* a3 = a2 + kstep; const char* b3 = b2 + kstep;
;             if (last && has_next) S.a_ready(nxt);
;             if constexpr (SP2) {
;             PG8_LDB(B0, 0, 0); PG8_LDB(B1, 0, 1); PG8_SCHED; PG8_LDA(At, 0, 0); PG8_STAGE(PG8_SA(1, 1), a1 + hstep, voffA);
;             PG8_WAIT_V(8); PG8_WAIT_L(0); PG8_BAR; PG8_MMA(0, 0, At, B0); PG8_MMA(0, 1, At, B1); PG8_BAR; PG8_SCHED;
;             PG8_LDA(At, 0, 1); PG8_STAGE(PG8_SB(0, 0), b2, voffB); PG8_STAGE(PG8_SB(0, 1), b2 + hstep, voffB); PG8_STAGE(PG8_SA(0, 0), a2, voffA);
;             PG8_WAIT_V(8); PG8_WAIT_L(0); PG8_BAR; PG8_MMA(1, 0, At, B0); PG8_MMA(1, 1, At, B1); PG8_BAR; PG8_SCHED;
.LBB0_195:
	s_ashr_i32 s19, s18, 31
	s_lshl_b64 s[20:21], s[18:19], 20
	s_add_u32 s20, s30, s20
	s_addc_u32 s21, s31, s21
	s_and_b64 s[44:45], s[6:7], exec
	s_cselect_b32 s5, s21, s57
	s_cselect_b32 s19, s20, s56
	s_ashr_i32 s17, s16, 31
	s_lshl_b64 s[44:45], s[16:17], 20
	s_add_u32 s44, s24, s44
	s_addc_u32 s45, s25, s45
	s_and_b64 s[60:61], s[6:7], exec
	s_cselect_b32 s17, s45, s59
	s_cselect_b32 s47, s44, s58
	s_add_u32 s56, s56, 0x84000
	s_addc_u32 s57, s57, 0
	s_add_u32 s87, s58, 0x8000
	s_addc_u32 s88, s59, 0
	s_mov_b32 s89, -2
	s_waitcnt lgkmcnt(0)
	ds_read_b128 v[220:223], v161
	ds_read_b128 v[224:227], v161 offset:1024
	ds_read_b128 v[228:231], v161 offset:2048
	ds_read_b128 v[232:235], v161 offset:3072
	ds_read_b128 v[236:239], v162
	ds_read_b128 v[240:243], v162 offset:1024
	ds_read_b128 v[244:247], v162 offset:2048
	ds_read_b128 v[248:251], v162 offset:3072
	s_add_u32 s58, s56, 0xfff84000
	s_addc_u32 s59, s57, -1
	s_cmp_eq_u32 s89, 28
	s_cselect_b32 s70, s19, s58
	s_cselect_b32 s71, s5, s59
	s_cselect_b32 s60, s47, s87
	s_cselect_b32 s61, s17, s88
	s_add_u32 s58, s70, 0x4000
	s_addc_u32 s59, s71, 0
	v_lshl_add_u64 v[178:179], s[56:57], 0, v[138:139]
	s_add_i32 m0, s72, 0xc000
	ds_read_b128 v[188:191], v163
	ds_read_b128 v[192:195], v163 offset:1024
	ds_read_b128 v[196:199], v163 offset:2048
	ds_read_b128 v[200:203], v163 offset:3072
	ds_read_b128 v[204:207], v163 offset:4096
	ds_read_b128 v[208:211], v163 offset:5120
	ds_read_b128 v[212:215], v163 offset:6144
	ds_read_b128 v[216:219], v163 offset:7168
	global_load_lds_dwordx4 v[178:179], off
	v_lshl_add_u64 v[178:179], s[56:57], 0, v[146:147]
	s_add_i32 m0, s72, 0xe000
	s_nop 0
	global_load_lds_dwordx4 v[178:179], off
	s_waitcnt vmcnt(8)
	s_waitcnt lgkmcnt(0)
	s_barrier
	s_setprio 1
	s_waitcnt lgkmcnt(0)
	v_mfma_f32_16x16x32_bf16 v[126:129], v[220:223], v[188:191], 0
	v_mfma_f32_16x16x32_bf16 v[126:129], v[224:227], v[192:195], v[126:129]
	v_mfma_f32_16x16x32_bf16 v[122:125], v[232:235], v[192:195], 0
	v_mfma_f32_16x16x32_bf16 v[122:125], v[228:231], v[188:191], v[122:125]
	v_mfma_f32_16x16x32_bf16 v[106:109], v[228:231], v[196:199], 0
	v_mfma_f32_16x16x32_bf16 v[106:109], v[232:235], v[200:203], v[106:109]
	v_mfma_f32_16x16x32_bf16 v[110:113], v[224:227], v[200:203], 0
	v_mfma_f32_16x16x32_bf16 v[110:113], v[220:223], v[196:199], v[110:113]
	v_mfma_f32_16x16x32_bf16 v[94:97], v[220:223], v[204:207], 0
	v_mfma_f32_16x16x32_bf16 v[94:97], v[224:227], v[208:211], v[94:97]
	v_mfma_f32_16x16x32_bf16 v[90:93], v[232:235], v[208:211], 0
	v_mfma_f32_16x16x32_bf16 v[90:93], v[228:231], v[204:207], v[90:93]
	v_mfma_f32_16x16x32_bf16 v[74:77], v[228:231], v[212:215], 0
	v_mfma_f32_16x16x32_bf16 v[74:77], v[232:235], v[216:219], v[74:77]
	v_mfma_f32_16x16x32_bf16 v[78:81], v[224:227], v[216:219], 0
	v_mfma_f32_16x16x32_bf16 v[78:81], v[220:223], v[212:215], v[78:81]
	s_setprio 0
	s_setprio 1
	v_mfma_f32_16x16x32_bf16 v[70:73], v[236:239], v[212:215], 0
	v_mfma_f32_16x16x32_bf16 v[70:73], v[240:243], v[216:219], v[70:73]
	v_mfma_f32_16x16x32_bf16 v[66:69], v[248:251], v[216:219], 0
	v_mfma_f32_16x16x32_bf16 v[66:69], v[244:247], v[212:215], v[66:69]
	v_mfma_f32_16x16x32_bf16 v[82:85], v[244:247], v[204:207], 0
	v_mfma_f32_16x16x32_bf16 v[82:85], v[248:251], v[208:211], v[82:85]
	v_mfma_f32_16x16x32_bf16 v[86:89], v[240:243], v[208:211], 0
	v_mfma_f32_16x16x32_bf16 v[86:89], v[236:239], v[204:207], v[86:89]
	v_mfma_f32_16x16x32_bf16 v[102:105], v[236:239], v[196:199], 0
	v_mfma_f32_16x16x32_bf16 v[102:105], v[240:243], v[200:203], v[102:105]
	v_mfma_f32_16x16x32_bf16 v[98:101], v[248:251], v[200:203], 0
	v_mfma_f32_16x16x32_bf16 v[98:101], v[244:247], v[196:199], v[98:101]
	v_mfma_f32_16x16x32_bf16 v[114:117], v[244:247], v[188:191], 0
	v_mfma_f32_16x16x32_bf16 v[114:117], v[248:251], v[192:195], v[114:117]
	v_mfma_f32_16x16x32_bf16 v[118:121], v[240:243], v[192:195], 0
	v_mfma_f32_16x16x32_bf16 v[118:121], v[236:239], v[188:191], v[118:121]
	s_setprio 0
	s_barrier
	s_add_i32 s90, s83, s15
	v_lshl_add_u64 v[178:179], s[60:61], 0, v[138:139]
	s_mov_b32 m0, s90
	ds_read_b128 v[188:191], v163 offset:16384
	ds_read_b128 v[192:195], v163 offset:17408
	ds_read_b128 v[196:199], v163 offset:18432
	ds_read_b128 v[200:203], v163 offset:19456
	ds_read_b128 v[204:207], v163 offset:20480
	ds_read_b128 v[208:211], v163 offset:21504
	ds_read_b128 v[212:215], v163 offset:22528
	ds_read_b128 v[216:219], v163 offset:23552
	global_load_lds_dwordx4 v[178:179], off
	s_add_i32 m0, s90, 0x2000
	s_add_u32 s90, s60, 0x80000
	v_lshl_add_u64 v[178:179], s[60:61], 0, v[140:141]
	s_addc_u32 s91, s61, 0
	s_add_i32 s92, s86, s15
	global_load_lds_dwordx4 v[178:179], off
	v_lshl_add_u64 v[178:179], s[90:91], 0, v[138:139]
	s_mov_b32 m0, s92
	s_nop 0
	global_load_lds_dwordx4 v[178:179], off
	v_lshl_add_u64 v[178:179], s[90:91], 0, v[140:141]
	s_add_i32 m0, s92, 0x2000
	s_nop 0
	global_load_lds_dwordx4 v[178:179], off
	v_lshl_add_u64 v[178:179], s[70:71], 0, v[138:139]
	s_mov_b32 m0, s72
	s_nop 0
	global_load_lds_dwordx4 v[178:179], off
	v_lshl_add_u64 v[178:179], s[70:71], 0, v[140:141]
	s_mov_b32 m0, s73
	s_nop 0
	global_load_lds_dwordx4 v[178:179], off
	s_waitcnt vmcnt(8)
	s_waitcnt lgkmcnt(0)
	s_barrier
; #define PG8_STAGE(bufoff, gbase, voff) do { _Pragma("unroll") for (int _i = 0; _i < 2; ++_i) \
;         __builtin_amdgcn_global_load_lds((const unsigned*)((const char*)(gbase) + (voff)[_i]), (PG8_LAS unsigned*)(lds + (bufoff) + ldsw + _i * 8192), 16, 0, 0); } while (0)
; #define PG8_LDA(dst, b, h) do { _Pragma("unroll") for (int m = 0; m < 4; ++m) _Pragma("unroll") for (int k = 0; k < 2; ++k) dst[m][k] = *(const PG8_LAS bf16x8*)(lds + PG8_SA(b, h) + aoff + m * 2048 + k * 1024); } while (0)
; #define PG8_LDB(dst, b, h) do { _Pragma("unroll") for (int n = 0; n < 2; ++n) _Pragma("unroll") for (int k = 0; k < 2; ++k) dst[n][k] = *(const PG8_LAS bf16x8*)(lds + PG8_SB(b, h) + boff + n * 2048 + k * 1024); } while (0)
; #define PG8_MMA(ai, bj, At, Bt) do { __builtin_amdgcn_s_setprio(1); _Pragma("unroll") for (int m = 0; m < 4; ++m) _Pragma("unroll") for (int n = 0; n < 2; ++n) _Pragma("unroll") for (int k = 0; k < 2; ++k) \
;         acc[ai][bj][m][n] = __builtin_amdgcn_mfma_f32_16x16x32_bf16(Bt[n][k], At[m][k], acc[ai][bj][m][n], 0, 0, 0); __builtin_amdgcn_s_setprio(0); } while (0)
; #define PG8_WAIT_V(n) asm volatile("s_waitcnt vmcnt(" #n ")" ::: "memory")
; #define PG8_WAIT_L(n) asm volatile("s_waitcnt lgkmcnt(" #n ")" ::: "memory")
; #define PG8_BAR __builtin_amdgcn_s_barrier()
; #define PG8_SCHED __builtin_amdgcn_sched_barrier(0)
; template <class Epi, class Sched, bool ALIGN_EPI = false, bool SP2 = false, bool RS = false, bool BPRE = false>
; __device__ __forceinline__ void gemm_phase(PG8_LAS unsigned char* lds, const Gemm g, const Sched& S, const Epi& E, const float* rs_ss = nullptr, PG8_LAS float* rs_tab = nullptr) {
;     ...
;             PG8_WAIT_V(8); PG8_WAIT_L(0); PG8_BAR; PG8_MMA(1, 0, At, B0); PG8_MMA(1, 1, At, B1); PG8_BAR; PG8_SCHED;
;             PG8_LDB(B0, 1, 0); PG8_LDB(B1, 1, 1); PG8_SCHED; PG8_LDA(At, 1, 0); PG8_STAGE(PG8_SA(0, 1), a2 + hstep, voffA);
;             PG8_WAIT_V(8); PG8_WAIT_L(0); PG8_BAR; PG8_MMA(0, 0, At, B0); PG8_MMA(0, 1, At, B1); PG8_BAR; PG8_SCHED;
	s_setprio 1
	s_waitcnt lgkmcnt(0)
	v_mfma_f32_16x16x32_bf16 v[62:65], v[220:223], v[188:191], 0
	v_mfma_f32_16x16x32_bf16 v[62:65], v[224:227], v[192:195], v[62:65]
	v_mfma_f32_16x16x32_bf16 v[58:61], v[232:235], v[192:195], 0
	v_mfma_f32_16x16x32_bf16 v[58:61], v[228:231], v[188:191], v[58:61]
	v_mfma_f32_16x16x32_bf16 v[42:45], v[228:231], v[196:199], 0
	v_mfma_f32_16x16x32_bf16 v[42:45], v[232:235], v[200:203], v[42:45]
	v_mfma_f32_16x16x32_bf16 v[46:49], v[224:227], v[200:203], 0
	v_mfma_f32_16x16x32_bf16 v[46:49], v[220:223], v[196:199], v[46:49]
	v_mfma_f32_16x16x32_bf16 v[30:33], v[220:223], v[204:207], 0
	v_mfma_f32_16x16x32_bf16 v[30:33], v[224:227], v[208:211], v[30:33]
	v_mfma_f32_16x16x32_bf16 v[26:29], v[232:235], v[208:211], 0
	v_mfma_f32_16x16x32_bf16 v[26:29], v[228:231], v[204:207], v[26:29]
	v_mfma_f32_16x16x32_bf16 v[10:13], v[228:231], v[212:215], 0
	v_mfma_f32_16x16x32_bf16 v[10:13], v[232:235], v[216:219], v[10:13]
	v_mfma_f32_16x16x32_bf16 v[14:17], v[224:227], v[216:219], 0
	v_mfma_f32_16x16x32_bf16 v[14:17], v[220:223], v[212:215], v[14:17]
	s_setprio 0
	s_setprio 1
	v_mfma_f32_16x16x32_bf16 v[6:9], v[236:239], v[212:215], 0
	v_mfma_f32_16x16x32_bf16 v[6:9], v[240:243], v[216:219], v[6:9]
	v_mfma_f32_16x16x32_bf16 v[2:5], v[248:251], v[216:219], 0
	v_mfma_f32_16x16x32_bf16 v[2:5], v[244:247], v[212:215], v[2:5]
	v_mfma_f32_16x16x32_bf16 v[18:21], v[244:247], v[204:207], 0
	v_mfma_f32_16x16x32_bf16 v[18:21], v[248:251], v[208:211], v[18:21]
	v_mfma_f32_16x16x32_bf16 v[22:25], v[240:243], v[208:211], 0
	v_mfma_f32_16x16x32_bf16 v[22:25], v[236:239], v[204:207], v[22:25]
	v_mfma_f32_16x16x32_bf16 v[38:41], v[236:239], v[196:199], 0
	v_mfma_f32_16x16x32_bf16 v[38:41], v[240:243], v[200:203], v[38:41]
	v_mfma_f32_16x16x32_bf16 v[34:37], v[248:251], v[200:203], 0
	v_mfma_f32_16x16x32_bf16 v[34:37], v[244:247], v[196:199], v[34:37]
	v_mfma_f32_16x16x32_bf16 v[50:53], v[244:247], v[188:191], 0
	v_mfma_f32_16x16x32_bf16 v[50:53], v[248:251], v[192:195], v[50:53]
	v_mfma_f32_16x16x32_bf16 v[54:57], v[240:243], v[192:195], 0
	v_mfma_f32_16x16x32_bf16 v[54:57], v[236:239], v[188:191], v[54:57]
	s_setprio 0
	s_barrier
	s_add_i32 s90, 0, 0x18000
	v_add_u32_e32 v143, s90, v160
	s_add_i32 s91, 0, 0x1c000
	ds_read_b128 v[220:223], v143
	ds_read_b128 v[224:227], v143 offset:1024
	ds_read_b128 v[228:231], v143 offset:2048
	ds_read_b128 v[232:235], v143 offset:3072
	v_add_u32_e32 v143, s91, v160
	ds_read_b128 v[236:239], v143
	ds_read_b128 v[240:243], v143 offset:1024
	ds_read_b128 v[244:247], v143 offset:2048
	ds_read_b128 v[248:251], v143 offset:3072
	s_add_u32 s70, s70, 0x80000
	s_addc_u32 s71, s71, 0
	s_mov_b32 m0, s74
	v_lshl_add_u64 v[178:179], s[70:71], 0, v[138:139]
	ds_read_b128 v[188:191], v163 offset:32768
	ds_read_b128 v[192:195], v163 offset:33792
	ds_read_b128 v[196:199], v163 offset:34816
	ds_read_b128 v[200:203], v163 offset:35840
	ds_read_b128 v[204:207], v163 offset:36864
	ds_read_b128 v[208:211], v163 offset:37888
	ds_read_b128 v[212:215], v163 offset:38912
	ds_read_b128 v[216:219], v163 offset:39936
	global_load_lds_dwordx4 v[178:179], off
	v_lshl_add_u64 v[178:179], s[70:71], 0, v[140:141]
	s_mov_b32 m0, s75
	s_nop 0
	global_load_lds_dwordx4 v[178:179], off
	s_waitcnt vmcnt(8)
	s_waitcnt lgkmcnt(0)
	s_barrier
	s_setprio 1
	s_waitcnt lgkmcnt(0)
	v_mfma_f32_16x16x32_bf16 v[126:129], v[220:223], v[188:191], v[126:129]
	v_mfma_f32_16x16x32_bf16 v[126:129], v[224:227], v[192:195], v[126:129]
	v_mfma_f32_16x16x32_bf16 v[122:125], v[232:235], v[192:195], v[122:125]
	v_mfma_f32_16x16x32_bf16 v[122:125], v[228:231], v[188:191], v[122:125]
	v_mfma_f32_16x16x32_bf16 v[106:109], v[228:231], v[196:199], v[106:109]
	v_mfma_f32_16x16x32_bf16 v[106:109], v[232:235], v[200:203], v[106:109]
	v_mfma_f32_16x16x32_bf16 v[110:113], v[224:227], v[200:203], v[110:113]
	v_mfma_f32_16x16x32_bf16 v[110:113], v[220:223], v[196:199], v[110:113]
	v_mfma_f32_16x16x32_bf16 v[94:97], v[220:223], v[204:207], v[94:97]
	v_mfma_f32_16x16x32_bf16 v[94:97], v[224:227], v[208:211], v[94:97]
	v_mfma_f32_16x16x32_bf16 v[90:93], v[232:235], v[208:211], v[90:93]
	v_mfma_f32_16x16x32_bf16 v[90:93], v[228:231], v[204:207], v[90:93]
	v_mfma_f32_16x16x32_bf16 v[74:77], v[228:231], v[212:215], v[74:77]
	v_mfma_f32_16x16x32_bf16 v[74:77], v[232:235], v[216:219], v[74:77]
	v_mfma_f32_16x16x32_bf16 v[78:81], v[224:227], v[216:219], v[78:81]
	v_mfma_f32_16x16x32_bf16 v[78:81], v[220:223], v[212:215], v[78:81]
	s_setprio 0
	s_setprio 1
	v_mfma_f32_16x16x32_bf16 v[70:73], v[236:239], v[212:215], v[70:73]
	v_mfma_f32_16x16x32_bf16 v[70:73], v[240:243], v[216:219], v[70:73]
	v_mfma_f32_16x16x32_bf16 v[66:69], v[248:251], v[216:219], v[66:69]
	v_mfma_f32_16x16x32_bf16 v[66:69], v[244:247], v[212:215], v[66:69]
	v_mfma_f32_16x16x32_bf16 v[82:85], v[244:247], v[204:207], v[82:85]
	v_mfma_f32_16x16x32_bf16 v[82:85], v[248:251], v[208:211], v[82:85]
	v_mfma_f32_16x16x32_bf16 v[86:89], v[240:243], v[208:211], v[86:89]
	v_mfma_f32_16x16x32_bf16 v[86:89], v[236:239], v[204:207], v[86:89]
	v_mfma_f32_16x16x32_bf16 v[102:105], v[236:239], v[196:199], v[102:105]
	v_mfma_f32_16x16x32_bf16 v[102:105], v[240:243], v[200:203], v[102:105]
	v_mfma_f32_16x16x32_bf16 v[98:101], v[248:251], v[200:203], v[98:101]
	v_mfma_f32_16x16x32_bf16 v[98:101], v[244:247], v[196:199], v[98:101]
	v_mfma_f32_16x16x32_bf16 v[114:117], v[244:247], v[188:191], v[114:117]
	v_mfma_f32_16x16x32_bf16 v[114:117], v[248:251], v[192:195], v[114:117]
	v_mfma_f32_16x16x32_bf16 v[118:121], v[240:243], v[192:195], v[118:121]
	v_mfma_f32_16x16x32_bf16 v[118:121], v[236:239], v[188:191], v[118:121]
	s_setprio 0
	s_barrier
; #define PG8_STAGE(bufoff, gbase, voff) do { _Pragma("unroll") for (int _i = 0; _i < 2; ++_i) \
;         __builtin_amdgcn_global_load_lds((const unsigned*)((const char*)(gbase) + (voff)[_i]), (PG8_LAS unsigned*)(lds + (bufoff) + ldsw + _i * 8192), 16, 0, 0); } while (0)
; #define PG8_LDA(dst, b, h) do { _Pragma("unroll") for (int m = 0; m < 4; ++m) _Pragma("unroll") for (int k = 0; k < 2; ++k) dst[m][k] = *(const PG8_LAS bf16x8*)(lds + PG8_SA(b, h) + aoff + m * 2048 + k * 1024); } while (0)
; #define PG8_LDB(dst, b, h) do { _Pragma("unroll") for (int n = 0; n < 2; ++n) _Pragma("unroll") for (int k = 0; k < 2; ++k) dst[n][k] = *(const PG8_LAS bf16x8*)(lds + PG8_SB(b, h) + boff + n * 2048 + k * 1024); } while (0)
; #define PG8_MMA(ai, bj, At, Bt) do { __builtin_amdgcn_s_setprio(1); _Pragma("unroll") for (int m = 0; m < 4; ++m) _Pragma("unroll") for (int n = 0; n < 2; ++n) _Pragma("unroll") for (int k = 0; k < 2; ++k) \
;         acc[ai][bj][m][n] = __builtin_amdgcn_mfma_f32_16x16x32_bf16(Bt[n][k], At[m][k], acc[ai][bj][m][n], 0, 0, 0); __builtin_amdgcn_s_setprio(0); } while (0)
; #define PG8_WAIT_V(n) asm volatile("s_waitcnt vmcnt(" #n ")" ::: "memory")
; #define PG8_WAIT_L(n) asm volatile("s_waitcnt lgkmcnt(" #n ")" ::: "memory")
; #define PG8_BAR __builtin_amdgcn_s_barrier()
; #define PG8_SCHED __builtin_amdgcn_sched_barrier(0)
; template <class Epi, class Sched, bool ALIGN_EPI = false, bool SP2 = false, bool RS = false, bool BPRE = false>
; __device__ __forceinline__ void gemm_phase(PG8_LAS unsigned char* lds, const Gemm g, const Sched& S, const Epi& E, const float* rs_ss = nullptr, PG8_LAS float* rs_tab = nullptr) {
;     ...
;             PG8_LDB(B0, 0, 0); PG8_LDB(B1, 0, 1); PG8_SCHED; PG8_LDA(At, 0, 0); PG8_STAGE(PG8_SA(1, 1), a1 + hstep, voffA);
;             PG8_WAIT_V(8); PG8_WAIT_L(0); PG8_BAR; PG8_MMA(0, 0, At, B0); PG8_MMA(0, 1, At, B1); PG8_BAR; PG8_SCHED;
;     ...
;             PG8_LDA(At, 1, 1); PG8_STAGE(PG8_SB(1, 0), b3, voffB); PG8_STAGE(PG8_SB(1, 1), b3 + hstep, voffB); PG8_STAGE(PG8_SA(1, 0), a3, voffA);
;             PG8_WAIT_V(8); PG8_WAIT_L(0); PG8_BAR; PG8_MMA(1, 0, At, B0); PG8_MMA(1, 1, At, B1); PG8_BAR; PG8_SCHED;
	s_add_u32 s70, s60, 0x4000
	s_addc_u32 s71, s61, 0
	s_add_i32 s90, s90, s15
	v_lshl_add_u64 v[178:179], s[70:71], 0, v[138:139]
	s_mov_b32 m0, s90
	ds_read_b128 v[188:191], v163 offset:49152
	ds_read_b128 v[192:195], v163 offset:50176
	ds_read_b128 v[196:199], v163 offset:51200
	ds_read_b128 v[200:203], v163 offset:52224
	ds_read_b128 v[204:207], v163 offset:53248
	ds_read_b128 v[208:211], v163 offset:54272
	ds_read_b128 v[212:215], v163 offset:55296
	ds_read_b128 v[216:219], v163 offset:56320
	global_load_lds_dwordx4 v[178:179], off
	s_add_i32 m0, s90, 0x2000
	s_add_u32 s60, s60, 0x84000
	v_lshl_add_u64 v[178:179], s[70:71], 0, v[140:141]
	s_addc_u32 s61, s61, 0
	s_add_i32 s70, s91, s15
	global_load_lds_dwordx4 v[178:179], off
	v_lshl_add_u64 v[178:179], s[60:61], 0, v[138:139]
	s_mov_b32 m0, s70
	s_nop 0
	global_load_lds_dwordx4 v[178:179], off
	v_lshl_add_u64 v[178:179], s[60:61], 0, v[140:141]
	s_add_i32 m0, s70, 0x2000
	s_nop 0
	global_load_lds_dwordx4 v[178:179], off
	v_lshl_add_u64 v[178:179], s[58:59], 0, v[138:139]
	s_mov_b32 m0, s79
	s_nop 0
	global_load_lds_dwordx4 v[178:179], off
	v_lshl_add_u64 v[178:179], s[58:59], 0, v[140:141]
	s_mov_b32 m0, s80
	s_nop 0
	global_load_lds_dwordx4 v[178:179], off
	s_waitcnt vmcnt(8)
	s_waitcnt lgkmcnt(0)
	s_barrier
	s_setprio 1
	s_waitcnt lgkmcnt(0)
	v_mfma_f32_16x16x32_bf16 v[62:65], v[220:223], v[188:191], v[62:65]
	v_mfma_f32_16x16x32_bf16 v[62:65], v[224:227], v[192:195], v[62:65]
	v_mfma_f32_16x16x32_bf16 v[58:61], v[232:235], v[192:195], v[58:61]
	v_mfma_f32_16x16x32_bf16 v[58:61], v[228:231], v[188:191], v[58:61]
	v_mfma_f32_16x16x32_bf16 v[42:45], v[228:231], v[196:199], v[42:45]
	v_mfma_f32_16x16x32_bf16 v[42:45], v[232:235], v[200:203], v[42:45]
	v_mfma_f32_16x16x32_bf16 v[46:49], v[224:227], v[200:203], v[46:49]
	v_mfma_f32_16x16x32_bf16 v[46:49], v[220:223], v[196:199], v[46:49]
	v_mfma_f32_16x16x32_bf16 v[30:33], v[220:223], v[204:207], v[30:33]
	v_mfma_f32_16x16x32_bf16 v[30:33], v[224:227], v[208:211], v[30:33]
	v_mfma_f32_16x16x32_bf16 v[26:29], v[232:235], v[208:211], v[26:29]
	v_mfma_f32_16x16x32_bf16 v[26:29], v[228:231], v[204:207], v[26:29]
	v_mfma_f32_16x16x32_bf16 v[10:13], v[228:231], v[212:215], v[10:13]
	v_mfma_f32_16x16x32_bf16 v[10:13], v[232:235], v[216:219], v[10:13]
	v_mfma_f32_16x16x32_bf16 v[14:17], v[224:227], v[216:219], v[14:17]
	v_mfma_f32_16x16x32_bf16 v[14:17], v[220:223], v[212:215], v[14:17]
	s_setprio 0
	s_setprio 1
	v_mfma_f32_16x16x32_bf16 v[6:9], v[236:239], v[212:215], v[6:9]
	v_mfma_f32_16x16x32_bf16 v[6:9], v[240:243], v[216:219], v[6:9]
	v_mfma_f32_16x16x32_bf16 v[2:5], v[248:251], v[216:219], v[2:5]
	v_mfma_f32_16x16x32_bf16 v[2:5], v[244:247], v[212:215], v[2:5]
	v_mfma_f32_16x16x32_bf16 v[18:21], v[244:247], v[204:207], v[18:21]
	v_mfma_f32_16x16x32_bf16 v[18:21], v[248:251], v[208:211], v[18:21]
	v_mfma_f32_16x16x32_bf16 v[22:25], v[240:243], v[208:211], v[22:25]
	v_mfma_f32_16x16x32_bf16 v[22:25], v[236:239], v[204:207], v[22:25]
	v_mfma_f32_16x16x32_bf16 v[38:41], v[236:239], v[196:199], v[38:41]
	v_mfma_f32_16x16x32_bf16 v[38:41], v[240:243], v[200:203], v[38:41]
	v_mfma_f32_16x16x32_bf16 v[34:37], v[248:251], v[200:203], v[34:37]
	v_mfma_f32_16x16x32_bf16 v[34:37], v[244:247], v[196:199], v[34:37]
	v_mfma_f32_16x16x32_bf16 v[50:53], v[244:247], v[188:191], v[50:53]
	v_mfma_f32_16x16x32_bf16 v[50:53], v[248:251], v[192:195], v[50:53]
	v_mfma_f32_16x16x32_bf16 v[54:57], v[240:243], v[192:195], v[54:57]
	v_mfma_f32_16x16x32_bf16 v[54:57], v[236:239], v[188:191], v[54:57]
	s_setprio 0
	s_barrier
	s_add_i32 s89, s89, 2
	s_add_u32 s56, s56, 0x8000
	s_addc_u32 s57, s57, 0
	s_add_u32 s87, s87, 0x8000
	s_addc_u32 s88, s88, 0
.LBB0_196:
	ds_read_b128 v[220:223], v161
	ds_read_b128 v[224:227], v161 offset:1024
	ds_read_b128 v[228:231], v161 offset:2048
	ds_read_b128 v[232:235], v161 offset:3072
	ds_read_b128 v[236:239], v162
	ds_read_b128 v[240:243], v162 offset:1024
	ds_read_b128 v[244:247], v162 offset:2048
	ds_read_b128 v[248:251], v162 offset:3072
	s_add_u32 s58, s56, 0xfff84000
	s_addc_u32 s59, s57, -1
	s_cmp_eq_u32 s89, 28
	s_cselect_b32 s70, s19, s58
	s_cselect_b32 s71, s5, s59
	s_cselect_b32 s60, s47, s87
	s_cselect_b32 s61, s17, s88
	s_add_u32 s58, s70, 0x4000
	s_addc_u32 s59, s71, 0
	v_lshl_add_u64 v[178:179], s[56:57], 0, v[138:139]
	s_add_i32 m0, s72, 0xc000
	ds_read_b128 v[188:191], v163
	ds_read_b128 v[192:195], v163 offset:1024
	ds_read_b128 v[196:199], v163 offset:2048
	ds_read_b128 v[200:203], v163 offset:3072
	ds_read_b128 v[204:207], v163 offset:4096
	ds_read_b128 v[208:211], v163 offset:5120
	ds_read_b128 v[212:215], v163 offset:6144
	ds_read_b128 v[216:219], v163 offset:7168
	global_load_lds_dwordx4 v[178:179], off
	v_lshl_add_u64 v[178:179], s[56:57], 0, v[146:147]
	s_add_i32 m0, s72, 0xe000
	s_nop 0
	global_load_lds_dwordx4 v[178:179], off
	s_waitcnt vmcnt(8)
	s_waitcnt lgkmcnt(0)
	s_barrier
; #define PG8_STAGE(bufoff, gbase, voff) do { _Pragma("unroll") for (int _i = 0; _i < 2; ++_i) \
;         __builtin_amdgcn_global_load_lds((const unsigned*)((const char*)(gbase) + (voff)[_i]), (PG8_LAS unsigned*)(lds + (bufoff) + ldsw + _i * 8192), 16, 0, 0); } while (0)
; #define PG8_LDA(dst, b, h) do { _Pragma("unroll") for (int m = 0; m < 4; ++m) _Pragma("unroll") for (int k = 0; k < 2; ++k) dst[m][k] = *(const PG8_LAS bf16x8*)(lds + PG8_SA(b, h) + aoff + m * 2048 + k * 1024); } while (0)
; #define PG8_MMA(ai, bj, At, Bt) do { __builtin_amdgcn_s_setprio(1); _Pragma("unroll") for (int m = 0; m < 4; ++m) _Pragma("unroll") for (int n = 0; n < 2; ++n) _Pragma("unroll") for (int k = 0; k < 2; ++k) \
;         acc[ai][bj][m][n] = __builtin_amdgcn_mfma_f32_16x16x32_bf16(Bt[n][k], At[m][k], acc[ai][bj][m][n], 0, 0, 0); __builtin_amdgcn_s_setprio(0); } while (0)
; #define PG8_WAIT_V(n) asm volatile("s_waitcnt vmcnt(" #n ")" ::: "memory")
; #define PG8_WAIT_L(n) asm volatile("s_waitcnt lgkmcnt(" #n ")" ::: "memory")
; #define PG8_BAR __builtin_amdgcn_s_barrier()
; #define PG8_SCHED __builtin_amdgcn_sched_barrier(0)
; template <class Epi, class Sched, bool ALIGN_EPI = false, bool SP2 = false, bool RS = false, bool BPRE = false>
; __device__ __forceinline__ void gemm_phase(PG8_LAS unsigned char* lds, const Gemm g, const Sched& S, const Epi& E, const float* rs_ss = nullptr, PG8_LAS float* rs_tab = nullptr) {
;     ...
;             PG8_WAIT_V(8); PG8_WAIT_L(0); PG8_BAR; PG8_MMA(0, 0, At, B0); PG8_MMA(0, 1, At, B1); PG8_BAR; PG8_SCHED;
;             PG8_LDA(At, 0, 1); PG8_STAGE(PG8_SB(0, 0), b2, voffB); PG8_STAGE(PG8_SB(0, 1), b2 + hstep, voffB); PG8_STAGE(PG8_SA(0, 0), a2, voffA);
;             PG8_WAIT_V(8); PG8_WAIT_L(0); PG8_BAR; PG8_MMA(1, 0, At, B0); PG8_MMA(1, 1, At, B1); PG8_BAR; PG8_SCHED;
	s_setprio 1
	s_waitcnt lgkmcnt(0)
	v_mfma_f32_16x16x32_bf16 v[126:129], v[220:223], v[188:191], v[126:129]
	v_mfma_f32_16x16x32_bf16 v[126:129], v[224:227], v[192:195], v[126:129]
	v_mfma_f32_16x16x32_bf16 v[122:125], v[232:235], v[192:195], v[122:125]
	v_mfma_f32_16x16x32_bf16 v[122:125], v[228:231], v[188:191], v[122:125]
	v_mfma_f32_16x16x32_bf16 v[106:109], v[228:231], v[196:199], v[106:109]
	v_mfma_f32_16x16x32_bf16 v[106:109], v[232:235], v[200:203], v[106:109]
	v_mfma_f32_16x16x32_bf16 v[110:113], v[224:227], v[200:203], v[110:113]
	v_mfma_f32_16x16x32_bf16 v[110:113], v[220:223], v[196:199], v[110:113]
	v_mfma_f32_16x16x32_bf16 v[94:97], v[220:223], v[204:207], v[94:97]
	v_mfma_f32_16x16x32_bf16 v[94:97], v[224:227], v[208:211], v[94:97]
	v_mfma_f32_16x16x32_bf16 v[90:93], v[232:235], v[208:211], v[90:93]
	v_mfma_f32_16x16x32_bf16 v[90:93], v[228:231], v[204:207], v[90:93]
	v_mfma_f32_16x16x32_bf16 v[74:77], v[228:231], v[212:215], v[74:77]
	v_mfma_f32_16x16x32_bf16 v[74:77], v[232:235], v[216:219], v[74:77]
	v_mfma_f32_16x16x32_bf16 v[78:81], v[224:227], v[216:219], v[78:81]
	v_mfma_f32_16x16x32_bf16 v[78:81], v[220:223], v[212:215], v[78:81]
	s_setprio 0
	s_setprio 1
	v_mfma_f32_16x16x32_bf16 v[70:73], v[236:239], v[212:215], v[70:73]
	v_mfma_f32_16x16x32_bf16 v[70:73], v[240:243], v[216:219], v[70:73]
	v_mfma_f32_16x16x32_bf16 v[66:69], v[248:251], v[216:219], v[66:69]
	v_mfma_f32_16x16x32_bf16 v[66:69], v[244:247], v[212:215], v[66:69]
	v_mfma_f32_16x16x32_bf16 v[82:85], v[244:247], v[204:207], v[82:85]
	v_mfma_f32_16x16x32_bf16 v[82:85], v[248:251], v[208:211], v[82:85]
	v_mfma_f32_16x16x32_bf16 v[86:89], v[240:243], v[208:211], v[86:89]
	v_mfma_f32_16x16x32_bf16 v[86:89], v[236:239], v[204:207], v[86:89]
	v_mfma_f32_16x16x32_bf16 v[102:105], v[236:239], v[196:199], v[102:105]
	v_mfma_f32_16x16x32_bf16 v[102:105], v[240:243], v[200:203], v[102:105]
	v_mfma_f32_16x16x32_bf16 v[98:101], v[248:251], v[200:203], v[98:101]
	v_mfma_f32_16x16x32_bf16 v[98:101], v[244:247], v[196:199], v[98:101]
	v_mfma_f32_16x16x32_bf16 v[114:117], v[244:247], v[188:191], v[114:117]
	v_mfma_f32_16x16x32_bf16 v[114:117], v[248:251], v[192:195], v[114:117]
	v_mfma_f32_16x16x32_bf16 v[118:121], v[240:243], v[192:195], v[118:121]
	v_mfma_f32_16x16x32_bf16 v[118:121], v[236:239], v[188:191], v[118:121]
	s_setprio 0
	s_barrier
	s_add_i32 s90, s83, s15
	v_lshl_add_u64 v[178:179], s[60:61], 0, v[138:139]
	s_mov_b32 m0, s90
	ds_read_b128 v[188:191], v163 offset:16384
	ds_read_b128 v[192:195], v163 offset:17408
	ds_read_b128 v[196:199], v163 offset:18432
	ds_read_b128 v[200:203], v163 offset:19456
	ds_read_b128 v[204:207], v163 offset:20480
	ds_read_b128 v[208:211], v163 offset:21504
	ds_read_b128 v[212:215], v163 offset:22528
	ds_read_b128 v[216:219], v163 offset:23552
	global_load_lds_dwordx4 v[178:179], off
	s_add_i32 m0, s90, 0x2000
	s_add_u32 s90, s60, 0x80000
	v_lshl_add_u64 v[178:179], s[60:61], 0, v[140:141]
	s_addc_u32 s91, s61, 0
	s_add_i32 s92, s86, s15
	global_load_lds_dwordx4 v[178:179], off
	v_lshl_add_u64 v[178:179], s[90:91], 0, v[138:139]
	s_mov_b32 m0, s92
	s_nop 0
	global_load_lds_dwordx4 v[178:179], off
	v_lshl_add_u64 v[178:179], s[90:91], 0, v[140:141]
	s_add_i32 m0, s92, 0x2000
	s_nop 0
	global_load_lds_dwordx4 v[178:179], off
	v_lshl_add_u64 v[178:179], s[70:71], 0, v[138:139]
	s_mov_b32 m0, s72
	s_nop 0
	global_load_lds_dwordx4 v[178:179], off
	v_lshl_add_u64 v[178:179], s[70:71], 0, v[140:141]
	s_mov_b32 m0, s73
	s_nop 0
	global_load_lds_dwordx4 v[178:179], off
	s_waitcnt vmcnt(8)
	s_waitcnt lgkmcnt(0)
	s_barrier
	s_setprio 1
	s_waitcnt lgkmcnt(0)
	v_mfma_f32_16x16x32_bf16 v[62:65], v[220:223], v[188:191], v[62:65]
	v_mfma_f32_16x16x32_bf16 v[62:65], v[224:227], v[192:195], v[62:65]
	v_mfma_f32_16x16x32_bf16 v[58:61], v[232:235], v[192:195], v[58:61]
	v_mfma_f32_16x16x32_bf16 v[58:61], v[228:231], v[188:191], v[58:61]
	v_mfma_f32_16x16x32_bf16 v[42:45], v[228:231], v[196:199], v[42:45]
	v_mfma_f32_16x16x32_bf16 v[42:45], v[232:235], v[200:203], v[42:45]
	v_mfma_f32_16x16x32_bf16 v[46:49], v[224:227], v[200:203], v[46:49]
	v_mfma_f32_16x16x32_bf16 v[46:49], v[220:223], v[196:199], v[46:49]
	v_mfma_f32_16x16x32_bf16 v[30:33], v[220:223], v[204:207], v[30:33]
	v_mfma_f32_16x16x32_bf16 v[30:33], v[224:227], v[208:211], v[30:33]
	v_mfma_f32_16x16x32_bf16 v[26:29], v[232:235], v[208:211], v[26:29]
	v_mfma_f32_16x16x32_bf16 v[26:29], v[228:231], v[204:207], v[26:29]
	v_mfma_f32_16x16x32_bf16 v[10:13], v[228:231], v[212:215], v[10:13]
	v_mfma_f32_16x16x32_bf16 v[10:13], v[232:235], v[216:219], v[10:13]
	v_mfma_f32_16x16x32_bf16 v[14:17], v[224:227], v[216:219], v[14:17]
	v_mfma_f32_16x16x32_bf16 v[14:17], v[220:223], v[212:215], v[14:17]
	s_setprio 0
	s_setprio 1
	v_mfma_f32_16x16x32_bf16 v[6:9], v[236:239], v[212:215], v[6:9]
	v_mfma_f32_16x16x32_bf16 v[6:9], v[240:243], v[216:219], v[6:9]
	v_mfma_f32_16x16x32_bf16 v[2:5], v[248:251], v[216:219], v[2:5]
	v_mfma_f32_16x16x32_bf16 v[2:5], v[244:247], v[212:215], v[2:5]
	v_mfma_f32_16x16x32_bf16 v[18:21], v[244:247], v[204:207], v[18:21]
	v_mfma_f32_16x16x32_bf16 v[18:21], v[248:251], v[208:211], v[18:21]
	v_mfma_f32_16x16x32_bf16 v[22:25], v[240:243], v[208:211], v[22:25]
	v_mfma_f32_16x16x32_bf16 v[22:25], v[236:239], v[204:207], v[22:25]
	v_mfma_f32_16x16x32_bf16 v[38:41], v[236:239], v[196:199], v[38:41]
	v_mfma_f32_16x16x32_bf16 v[38:41], v[240:243], v[200:203], v[38:41]
	v_mfma_f32_16x16x32_bf16 v[34:37], v[248:251], v[200:203], v[34:37]
	v_mfma_f32_16x16x32_bf16 v[34:37], v[244:247], v[196:199], v[34:37]
	v_mfma_f32_16x16x32_bf16 v[50:53], v[244:247], v[188:191], v[50:53]
	v_mfma_f32_16x16x32_bf16 v[50:53], v[248:251], v[192:195], v[50:53]
	v_mfma_f32_16x16x32_bf16 v[54:57], v[240:243], v[192:195], v[54:57]
	v_mfma_f32_16x16x32_bf16 v[54:57], v[236:239], v[188:191], v[54:57]
	s_setprio 0
	s_barrier
; #define PG8_STAGE(bufoff, gbase, voff) do { _Pragma("unroll") for (int _i = 0; _i < 2; ++_i) \
;         __builtin_amdgcn_global_load_lds((const unsigned*)((const char*)(gbase) + (voff)[_i]), (PG8_LAS unsigned*)(lds + (bufoff) + ldsw + _i * 8192), 16, 0, 0); } while (0)
; #define PG8_LDA(dst, b, h) do { _Pragma("unroll") for (int m = 0; m < 4; ++m) _Pragma("unroll") for (int k = 0; k < 2; ++k) dst[m][k] = *(const PG8_LAS bf16x8*)(lds + PG8_SA(b, h) + aoff + m * 2048 + k * 1024); } while (0)
; #define PG8_LDB(dst, b, h) do { _Pragma("unroll") for (int n = 0; n < 2; ++n) _Pragma("unroll") for (int k = 0; k < 2; ++k) dst[n][k] = *(const PG8_LAS bf16x8*)(lds + PG8_SB(b, h) + boff + n * 2048 + k * 1024); } while (0)
; #define PG8_MMA(ai, bj, At, Bt) do { __builtin_amdgcn_s_setprio(1); _Pragma("unroll") for (int m = 0; m < 4; ++m) _Pragma("unroll") for (int n = 0; n < 2; ++n) _Pragma("unroll") for (int k = 0; k < 2; ++k) \
;         acc[ai][bj][m][n] = __builtin_amdgcn_mfma_f32_16x16x32_bf16(Bt[n][k], At[m][k], acc[ai][bj][m][n], 0, 0, 0); __builtin_amdgcn_s_setprio(0); } while (0)
; #define PG8_WAIT_V(n) asm volatile("s_waitcnt vmcnt(" #n ")" ::: "memory")
; #define PG8_WAIT_L(n) asm volatile("s_waitcnt lgkmcnt(" #n ")" ::: "memory")
; #define PG8_BAR __builtin_amdgcn_s_barrier()
; #define PG8_SCHED __builtin_amdgcn_sched_barrier(0)
; template <class Epi, class Sched, bool ALIGN_EPI = false, bool SP2 = false, bool RS = false, bool BPRE = false>
; __device__ __forceinline__ void gemm_phase(PG8_LAS unsigned char* lds, const Gemm g, const Sched& S, const Epi& E, const float* rs_ss = nullptr, PG8_LAS float* rs_tab = nullptr) {
;     ...
;             PG8_LDB(B0, 1, 0); PG8_LDB(B1, 1, 1); PG8_SCHED; PG8_LDA(At, 1, 0); PG8_STAGE(PG8_SA(0, 1), a2 + hstep, voffA);
;             PG8_WAIT_V(8); PG8_WAIT_L(0); PG8_BAR; PG8_MMA(0, 0, At, B0); PG8_MMA(0, 1, At, B1); PG8_BAR; PG8_SCHED;
	s_add_i32 s90, 0, 0x18000
	v_add_u32_e32 v143, s90, v160
	s_add_i32 s91, 0, 0x1c000
	ds_read_b128 v[220:223], v143
	ds_read_b128 v[224:227], v143 offset:1024
	ds_read_b128 v[228:231], v143 offset:2048
	ds_read_b128 v[232:235], v143 offset:3072
	v_add_u32_e32 v143, s91, v160
	ds_read_b128 v[236:239], v143
	ds_read_b128 v[240:243], v143 offset:1024
	ds_read_b128 v[244:247], v143 offset:2048
	ds_read_b128 v[248:251], v143 offset:3072
	s_add_u32 s70, s70, 0x80000
	s_addc_u32 s71, s71, 0
	s_mov_b32 m0, s74
	v_lshl_add_u64 v[178:179], s[70:71], 0, v[138:139]
	ds_read_b128 v[188:191], v163 offset:32768
	ds_read_b128 v[192:195], v163 offset:33792
	ds_read_b128 v[196:199], v163 offset:34816
	ds_read_b128 v[200:203], v163 offset:35840
	ds_read_b128 v[204:207], v163 offset:36864
	ds_read_b128 v[208:211], v163 offset:37888
	ds_read_b128 v[212:215], v163 offset:38912
	ds_read_b128 v[216:219], v163 offset:39936
	global_load_lds_dwordx4 v[178:179], off
	v_lshl_add_u64 v[178:179], s[70:71], 0, v[140:141]
	s_mov_b32 m0, s75
	s_nop 0
	global_load_lds_dwordx4 v[178:179], off
	s_waitcnt vmcnt(8)
	s_waitcnt lgkmcnt(0)
	s_barrier
	s_setprio 1
	s_waitcnt lgkmcnt(0)
	v_mfma_f32_16x16x32_bf16 v[126:129], v[220:223], v[188:191], v[126:129]
	v_mfma_f32_16x16x32_bf16 v[126:129], v[224:227], v[192:195], v[126:129]
	v_mfma_f32_16x16x32_bf16 v[122:125], v[232:235], v[192:195], v[122:125]
	v_mfma_f32_16x16x32_bf16 v[122:125], v[228:231], v[188:191], v[122:125]
	v_mfma_f32_16x16x32_bf16 v[106:109], v[228:231], v[196:199], v[106:109]
	v_mfma_f32_16x16x32_bf16 v[106:109], v[232:235], v[200:203], v[106:109]
	v_mfma_f32_16x16x32_bf16 v[110:113], v[224:227], v[200:203], v[110:113]
	v_mfma_f32_16x16x32_bf16 v[110:113], v[220:223], v[196:199], v[110:113]
	v_mfma_f32_16x16x32_bf16 v[94:97], v[220:223], v[204:207], v[94:97]
	v_mfma_f32_16x16x32_bf16 v[94:97], v[224:227], v[208:211], v[94:97]
	v_mfma_f32_16x16x32_bf16 v[90:93], v[232:235], v[208:211], v[90:93]
	v_mfma_f32_16x16x32_bf16 v[90:93], v[228:231], v[204:207], v[90:93]
	v_mfma_f32_16x16x32_bf16 v[74:77], v[228:231], v[212:215], v[74:77]
	v_mfma_f32_16x16x32_bf16 v[74:77], v[232:235], v[216:219], v[74:77]
	v_mfma_f32_16x16x32_bf16 v[78:81], v[224:227], v[216:219], v[78:81]
	v_mfma_f32_16x16x32_bf16 v[78:81], v[220:223], v[212:215], v[78:81]
	s_setprio 0
	s_setprio 1
	v_mfma_f32_16x16x32_bf16 v[70:73], v[236:239], v[212:215], v[70:73]
	v_mfma_f32_16x16x32_bf16 v[70:73], v[240:243], v[216:219], v[70:73]
	v_mfma_f32_16x16x32_bf16 v[66:69], v[248:251], v[216:219], v[66:69]
	v_mfma_f32_16x16x32_bf16 v[66:69], v[244:247], v[212:215], v[66:69]
	v_mfma_f32_16x16x32_bf16 v[82:85], v[244:247], v[204:207], v[82:85]
	v_mfma_f32_16x16x32_bf16 v[82:85], v[248:251], v[208:211], v[82:85]
	v_mfma_f32_16x16x32_bf16 v[86:89], v[240:243], v[208:211], v[86:89]
	v_mfma_f32_16x16x32_bf16 v[86:89], v[236:239], v[204:207], v[86:89]
	v_mfma_f32_16x16x32_bf16 v[102:105], v[236:239], v[196:199], v[102:105]
	v_mfma_f32_16x16x32_bf16 v[102:105], v[240:243], v[200:203], v[102:105]
	v_mfma_f32_16x16x32_bf16 v[98:101], v[248:251], v[200:203], v[98:101]
	v_mfma_f32_16x16x32_bf16 v[98:101], v[244:247], v[196:199], v[98:101]
	v_mfma_f32_16x16x32_bf16 v[114:117], v[244:247], v[188:191], v[114:117]
	v_mfma_f32_16x16x32_bf16 v[114:117], v[248:251], v[192:195], v[114:117]
	v_mfma_f32_16x16x32_bf16 v[118:121], v[240:243], v[192:195], v[118:121]
	v_mfma_f32_16x16x32_bf16 v[118:121], v[236:239], v[188:191], v[118:121]
	s_setprio 0
	s_barrier
; #define PG8_STAGE(bufoff, gbase, voff) do { _Pragma("unroll") for (int _i = 0; _i < 2; ++_i) \
;         __builtin_amdgcn_global_load_lds((const unsigned*)((const char*)(gbase) + (voff)[_i]), (PG8_LAS unsigned*)(lds + (bufoff) + ldsw + _i * 8192), 16, 0, 0); } while (0)
; #define PG8_LDA(dst, b, h) do { _Pragma("unroll") for (int m = 0; m < 4; ++m) _Pragma("unroll") for (int k = 0; k < 2; ++k) dst[m][k] = *(const PG8_LAS bf16x8*)(lds + PG8_SA(b, h) + aoff + m * 2048 + k * 1024); } while (0)
; #define PG8_MMA(ai, bj, At, Bt) do { __builtin_amdgcn_s_setprio(1); _Pragma("unroll") for (int m = 0; m < 4; ++m) _Pragma("unroll") for (int n = 0; n < 2; ++n) _Pragma("unroll") for (int k = 0; k < 2; ++k) \
;         acc[ai][bj][m][n] = __builtin_amdgcn_mfma_f32_16x16x32_bf16(Bt[n][k], At[m][k], acc[ai][bj][m][n], 0, 0, 0); __builtin_amdgcn_s_setprio(0); } while (0)
; #define PG8_WAIT_V(n) asm volatile("s_waitcnt vmcnt(" #n ")" ::: "memory")
; #define PG8_WAIT_L(n) asm volatile("s_waitcnt lgkmcnt(" #n ")" ::: "memory")
; #define PG8_BAR __builtin_amdgcn_s_barrier()
; #define PG8_SCHED __builtin_amdgcn_sched_barrier(0)
; template <class Epi, class Sched, bool ALIGN_EPI = false, bool SP2 = false, bool RS = false, bool BPRE = false>
; __device__ __forceinline__ void gemm_phase(PG8_LAS unsigned char* lds, const Gemm g, const Sched& S, const Epi& E, const float* rs_ss = nullptr, PG8_LAS float* rs_tab = nullptr) {
;     ...
;             PG8_LDA(At, 1, 1); PG8_STAGE(PG8_SB(1, 0), b3, voffB); PG8_STAGE(PG8_SB(1, 1), b3 + hstep, voffB); PG8_STAGE(PG8_SA(1, 0), a3, voffA);
;             PG8_WAIT_V(8); PG8_WAIT_L(0); PG8_BAR; PG8_MMA(1, 0, At, B0); PG8_MMA(1, 1, At, B1); PG8_BAR; PG8_SCHED;
;     ...
;         if constexpr (ALIGN_EPI) { if (wr == 0) PG8_BAR; }
	s_add_u32 s70, s60, 0x4000
	s_addc_u32 s71, s61, 0
	s_add_i32 s90, s90, s15
	v_lshl_add_u64 v[178:179], s[70:71], 0, v[138:139]
	s_mov_b32 m0, s90
	ds_read_b128 v[188:191], v163 offset:49152
	ds_read_b128 v[192:195], v163 offset:50176
	ds_read_b128 v[196:199], v163 offset:51200
	ds_read_b128 v[200:203], v163 offset:52224
	ds_read_b128 v[204:207], v163 offset:53248
	ds_read_b128 v[208:211], v163 offset:54272
	ds_read_b128 v[212:215], v163 offset:55296
	ds_read_b128 v[216:219], v163 offset:56320
	global_load_lds_dwordx4 v[178:179], off
	s_add_i32 m0, s90, 0x2000
	s_add_u32 s60, s60, 0x84000
	v_lshl_add_u64 v[178:179], s[70:71], 0, v[140:141]
	s_addc_u32 s61, s61, 0
	s_add_i32 s70, s91, s15
	global_load_lds_dwordx4 v[178:179], off
	v_lshl_add_u64 v[178:179], s[60:61], 0, v[138:139]
	s_mov_b32 m0, s70
	s_nop 0
	global_load_lds_dwordx4 v[178:179], off
	v_lshl_add_u64 v[178:179], s[60:61], 0, v[140:141]
	s_add_i32 m0, s70, 0x2000
	s_nop 0
	global_load_lds_dwordx4 v[178:179], off
	v_lshl_add_u64 v[178:179], s[58:59], 0, v[138:139]
	s_mov_b32 m0, s79
	s_nop 0
	global_load_lds_dwordx4 v[178:179], off
	v_lshl_add_u64 v[178:179], s[58:59], 0, v[140:141]
	s_mov_b32 m0, s80
	s_nop 0
	global_load_lds_dwordx4 v[178:179], off
	s_waitcnt vmcnt(8)
	s_waitcnt lgkmcnt(0)
	s_barrier
	s_setprio 1
	s_waitcnt lgkmcnt(0)
	v_mfma_f32_16x16x32_bf16 v[62:65], v[220:223], v[188:191], v[62:65]
	v_mfma_f32_16x16x32_bf16 v[62:65], v[224:227], v[192:195], v[62:65]
	v_mfma_f32_16x16x32_bf16 v[58:61], v[232:235], v[192:195], v[58:61]
	v_mfma_f32_16x16x32_bf16 v[58:61], v[228:231], v[188:191], v[58:61]
	v_mfma_f32_16x16x32_bf16 v[42:45], v[228:231], v[196:199], v[42:45]
	v_mfma_f32_16x16x32_bf16 v[42:45], v[232:235], v[200:203], v[42:45]
	v_mfma_f32_16x16x32_bf16 v[46:49], v[224:227], v[200:203], v[46:49]
	v_mfma_f32_16x16x32_bf16 v[46:49], v[220:223], v[196:199], v[46:49]
	v_mfma_f32_16x16x32_bf16 v[30:33], v[220:223], v[204:207], v[30:33]
	v_mfma_f32_16x16x32_bf16 v[30:33], v[224:227], v[208:211], v[30:33]
	v_mfma_f32_16x16x32_bf16 v[26:29], v[232:235], v[208:211], v[26:29]
	v_mfma_f32_16x16x32_bf16 v[26:29], v[228:231], v[204:207], v[26:29]
	v_mfma_f32_16x16x32_bf16 v[10:13], v[228:231], v[212:215], v[10:13]
	v_mfma_f32_16x16x32_bf16 v[10:13], v[232:235], v[216:219], v[10:13]
	v_mfma_f32_16x16x32_bf16 v[14:17], v[224:227], v[216:219], v[14:17]
	v_mfma_f32_16x16x32_bf16 v[14:17], v[220:223], v[212:215], v[14:17]
	s_setprio 0
	s_setprio 1
	v_mfma_f32_16x16x32_bf16 v[6:9], v[236:239], v[212:215], v[6:9]
	v_mfma_f32_16x16x32_bf16 v[6:9], v[240:243], v[216:219], v[6:9]
	v_mfma_f32_16x16x32_bf16 v[2:5], v[248:251], v[216:219], v[2:5]
	v_mfma_f32_16x16x32_bf16 v[2:5], v[244:247], v[212:215], v[2:5]
	v_mfma_f32_16x16x32_bf16 v[18:21], v[244:247], v[204:207], v[18:21]
	v_mfma_f32_16x16x32_bf16 v[18:21], v[248:251], v[208:211], v[18:21]
	v_mfma_f32_16x16x32_bf16 v[22:25], v[240:243], v[208:211], v[22:25]
	v_mfma_f32_16x16x32_bf16 v[22:25], v[236:239], v[204:207], v[22:25]
	v_mfma_f32_16x16x32_bf16 v[38:41], v[236:239], v[196:199], v[38:41]
	v_mfma_f32_16x16x32_bf16 v[38:41], v[240:243], v[200:203], v[38:41]
	v_mfma_f32_16x16x32_bf16 v[34:37], v[248:251], v[200:203], v[34:37]
	v_mfma_f32_16x16x32_bf16 v[34:37], v[244:247], v[196:199], v[34:37]
	v_mfma_f32_16x16x32_bf16 v[50:53], v[244:247], v[188:191], v[50:53]
	v_mfma_f32_16x16x32_bf16 v[50:53], v[248:251], v[192:195], v[50:53]
	v_mfma_f32_16x16x32_bf16 v[54:57], v[240:243], v[192:195], v[54:57]
	v_mfma_f32_16x16x32_bf16 v[54:57], v[236:239], v[188:191], v[54:57]
	s_setprio 0
	s_barrier
	s_add_i32 s89, s89, 2
	s_add_u32 s56, s56, 0x8000
	s_addc_u32 s57, s57, 0
	s_add_u32 s87, s87, 0x8000
	s_addc_u32 s88, s88, 0
	s_cmp_gt_u32 s89, 29
	s_cbranch_scc0 .LBB0_196
	s_and_b64 vcc, exec, s[12:13]
	s_cbranch_vccz .LBB0_199
	s_barrier
